# NSA loop software pipelining: K/V tiles staged one step ahead into a 3-slot LDS ring, QK MFMAs of tile t+1 interleaved into the exp section of tile t (OCMP prefetch dropped to free fragment registers)
# baseline (speedup 1.0000x reference)
; #define LAS __attribute__((address_space(3)))
; DI float sigmoidf_(float x) { return __builtin_amdgcn_rcpf(1.0f + __expf(-x)); }
; #define MFMA32(a, b, c) __builtin_amdgcn_mfma_f32_32x32x16_bf16((a), (b), (c), 0, 0, 0)
; DI void fs_reset(FState& st) { st.o0 = f16zero(); st.o1 = f16zero(); st.m = NINF; st.l = 0.f; }
; DI void flash_qk(const LAS unsigned char* kb, const bf16x8 (&qf)[4], f32x16& p0, f32x16& p1, int r32, int h) {
;     p0 = f16zero(); p1 = f16zero();
;     const int sw = (r32 >> 1) & 7;
; #pragma unroll
;     for (int s = 0; s < 4; ++s) {
;         const int off = r32 * 128 + (((2 * s + h) ^ sw) << 4);
;         const bf16x8 a0 = *(const LAS bf16x8*)(kb + off), a1 = *(const LAS bf16x8*)(kb + off + 4096);
;         p0 = MFMA32(a0, qf[s], p0); p1 = MFMA32(a1, qf[s], p1);
;     }
; DI void nsa_task(LAS unsigned char* lds, const bf16_t* Z, const unsigned* selm, const bf16_t* OCMP, bf16_t* YA, int b, int hk, int c, int tid, int wave, int lane) {
;     ...
;     const float g_cmp = sigmoidf_(bf2f(zr[ZC_GA + head])), g_slc = sigmoidf_(bf2f(zr[ZC_GA + 8 + head])), g_win = sigmoidf_(bf2f(zr[ZC_GA + 16 + head]));
;     f32x16 y0 = f16zero(), y1 = f16zero();
;     FState st; fs_reset(st);
;     const int nsel = EN_SLC ? c + 1 : 0, nwin = EN_WIN ? (c + 1 < 9 ? c + 1 : 9) : 0, ntot = nsel + nwin;
;     const int skey = tid >> 3, sch = tid & 7;
;     const int kdst = skey * 128 + ((sch ^ ((skey >> 1) & 7)) << 4), vdst = 8192 + skey * 128 + ((sch * 16) ^ (((skey >> 1) & 1) << 6));
;     const bf16_t* sbase = Z + ((size_t)b * SEQ + skey) * NZ + hk * 64 + sch * 8;
;     u32x4 kA = {0u, 0u, 0u, 0u}, vA = kA, kB = kA, vB = kA, kC = kA, vC = kA;
.LBB0_740:
	s_waitcnt vmcnt(3)
	v_lshlrev_b32_e32 v5, 16, v5
	v_mul_f32_e32 v5, 0xbfb8aa3b, v5
	v_exp_f32_e32 v5, v5
	v_lshlrev_b32_e32 v195, 6, v4
	v_lshlrev_b32_e32 v4, 7, v194
	v_lshlrev_b32_e32 v6, 4, v205
	v_add_f32_e32 v5, 1.0, v5
	v_rcp_f32_e32 v197, v5
	v_lshlrev_b32_e32 v5, 6, v206
	v_and_b32_e32 v5, 64, v5
	v_mov_b32_e32 v16, v3
	v_mov_b32_e32 v17, v3
	v_and_or_b32 v205, v6, s66, v4
	v_lshlrev_b32_e32 v206, 4, v207
	v_lshlrev_b32_e32 v207, 4, v208
	v_lshlrev_b32_e32 v208, 4, v209
	v_lshlrev_b32_e32 v209, 4, v212
	s_add_i32 s4, s50, s69
	v_bitop3_b32 v212, v5, v4, v2 bitop3:0xde
	v_mov_b32_e32 v2, v3
	v_mov_b32_e32 v4, v3
	v_mov_b32_e32 v5, v3
	v_mov_b32_e32 v6, v3
	v_mov_b32_e32 v7, v3
	v_mov_b32_e32 v8, v3
	v_mov_b32_e32 v9, v3
	v_mov_b32_e32 v10, v3
	v_mov_b32_e32 v11, v3
	v_mov_b32_e32 v12, v3
	v_mov_b32_e32 v13, v3
	v_mov_b32_e32 v14, v3
	v_mov_b32_e32 v15, v3
	v_mov_b64_e32 v[80:81], v[16:17]
	v_mov_b64_e32 v[64:65], v[16:17]
	v_mov_b64_e32 v[48:49], v[16:17]
	v_mov_b64_e32 v[32:33], v[16:17]
	v_lshlrev_b32_e32 v194, 2, v210
	v_add_u32_e32 v210, 0xfffffe00, v190
	v_lshlrev_b32_e32 v211, 7, v211
	s_add_i32 s52, s4, -5
	s_mov_b32 s53, 0
	v_sub_u32_e32 v213, 0, v202
	s_sub_i32 s70, 0, s69
	s_add_i32 s71, s69, -2
	s_add_i32 s72, s69, -1
	v_mov_b32_e32 v214, 0
	v_mov_b32_e32 v216, 0xff800000
	s_mov_b32 s74, 0
	v_mov_b64_e32 v[78:79], v[14:15]
	v_mov_b64_e32 v[76:77], v[12:13]
	v_mov_b64_e32 v[74:75], v[10:11]
	v_mov_b64_e32 v[72:73], v[8:9]
	v_mov_b64_e32 v[70:71], v[6:7]
	v_mov_b64_e32 v[68:69], v[4:5]
	v_mov_b64_e32 v[66:67], v[2:3]
	v_mov_b64_e32 v[62:63], v[14:15]
	v_mov_b64_e32 v[60:61], v[12:13]
	v_mov_b64_e32 v[58:59], v[10:11]
	v_mov_b64_e32 v[56:57], v[8:9]
	v_mov_b64_e32 v[54:55], v[6:7]
	v_mov_b64_e32 v[52:53], v[4:5]
	v_mov_b64_e32 v[50:51], v[2:3]
	v_mov_b64_e32 v[46:47], v[14:15]
	v_mov_b64_e32 v[44:45], v[12:13]
	v_mov_b64_e32 v[42:43], v[10:11]
	v_mov_b64_e32 v[40:41], v[8:9]
	v_mov_b64_e32 v[38:39], v[6:7]
	v_mov_b64_e32 v[36:37], v[4:5]
	v_mov_b64_e32 v[34:35], v[2:3]
	v_mov_b64_e32 v[30:31], v[14:15]
	v_mov_b64_e32 v[28:29], v[12:13]
	v_mov_b64_e32 v[26:27], v[10:11]
	v_mov_b64_e32 v[24:25], v[8:9]
	v_mov_b64_e32 v[22:23], v[6:7]
	v_mov_b64_e32 v[20:21], v[4:5]
	v_mov_b64_e32 v[18:19], v[2:3]
	ds_write_b128 v205, v[162:165]
	ds_write_b128 v212, v[166:169] offset:8192
	v_add_u32_e32 v221, v201, v206
	v_add_u32_e32 v222, v201, v207
	v_add_u32_e32 v223, v201, v208
	v_add_u32_e32 v224, v201, v209
	s_waitcnt lgkmcnt(0)
	s_barrier
	ds_read_b128 v[226:229], v221
	ds_read_b128 v[230:233], v221 offset:4096
	ds_read_b128 v[234:237], v222
	ds_read_b128 v[238:241], v222 offset:4096
	s_waitcnt lgkmcnt(3)
	v_mfma_f32_32x32x16_bf16 v[130:145], v[226:229], v[146:149], 0
	s_waitcnt lgkmcnt(2)
	v_mfma_f32_32x32x16_bf16 v[114:129], v[230:233], v[146:149], 0
	ds_read_b128 v[226:229], v223
	ds_read_b128 v[230:233], v223 offset:4096
	s_waitcnt lgkmcnt(3)
	v_mfma_f32_32x32x16_bf16 v[130:145], v[234:237], v[150:153], v[130:145]
	s_waitcnt lgkmcnt(2)
	v_mfma_f32_32x32x16_bf16 v[114:129], v[238:241], v[150:153], v[114:129]
	ds_read_b128 v[234:237], v224
	ds_read_b128 v[238:241], v224 offset:4096
	s_waitcnt lgkmcnt(3)
	v_mfma_f32_32x32x16_bf16 v[130:145], v[226:229], v[154:157], v[130:145]
	s_waitcnt lgkmcnt(2)
	v_mfma_f32_32x32x16_bf16 v[114:129], v[230:233], v[154:157], v[114:129]
	s_waitcnt lgkmcnt(1)
	v_mfma_f32_32x32x16_bf16 v[130:145], v[234:237], v[158:161], v[130:145]
	s_waitcnt lgkmcnt(0)
	v_mfma_f32_32x32x16_bf16 v[114:129], v[238:241], v[158:161], v[114:129]
.LBB0_741:
	s_mov_b32 s76, 0
	s_add_i32 s73, s74, 3
	s_cmp_ge_u32 s73, s51
	s_cselect_b64 s[6:7], -1, 0
	s_waitcnt vmcnt(1)
	ds_write_b128 v205, v[170:173] offset:16384
	s_waitcnt vmcnt(0)
	ds_write_b128 v212, v[174:177] offset:24576
	s_waitcnt lgkmcnt(0)
	s_barrier
	s_cmp_lg_u32 s74, 0
	s_cbranch_scc1 .Lnsp_not3
	s_and_b64 vcc, exec, s[6:7]
	s_cbranch_vccnz .Lnsp_not3
	s_cmp_gt_u32 s73, s69
	s_cselect_b64 s[4:5], -1, 0
	s_add_i32 s8, s52, 2
	s_and_b64 s[4:5], s[4:5], exec
	s_cselect_b32 s8, s8, s73
	s_cselect_b32 s16, 0x1000, s65
	s_cselect_b32 s4, s64, 0x500
	s_lshl_b32 s8, s8, 6
	s_mov_b32 s5, s17
	v_mad_i64_i32 v[4:5], s[8:9], s8, v199, v[192:193]
	v_lshl_add_u64 v[6:7], v[4:5], 0, s[4:5]
	v_lshl_add_u64 v[4:5], v[4:5], 0, s[16:17]
	global_load_dwordx4 v[162:165], v[6:7], off
	global_load_dwordx4 v[166:169], v[4:5], off
.Lnsp_not3:
	s_add_i32 s4, s74, 4
	s_cmp_ge_u32 s4, s51
	s_cbranch_scc1 .LBB0_743
	s_cmp_gt_u32 s4, s69
	s_cselect_b64 s[8:9], -1, 0
	s_add_i32 s5, s52, 1
	s_and_b64 s[8:9], s[8:9], exec
	s_cselect_b32 s4, s5, s4
	s_cselect_b32 s16, 0x1000, s65
	s_cselect_b32 s8, s64, 0x500
	s_lshl_b32 s4, s4, 6
	s_mov_b32 s9, s17
	v_mad_i64_i32 v[4:5], s[4:5], s4, v199, v[192:193]
	v_lshl_add_u64 v[6:7], v[4:5], 0, s[8:9]
	v_lshl_add_u64 v[4:5], v[4:5], 0, s[16:17]
	global_load_dwordx4 v[170:173], v[6:7], off
	global_load_dwordx4 v[174:177], v[4:5], off

.LBB0_745:
	s_add_i32 s10, s52, 5
	s_cmp_gt_u32 s74, s69
	s_cselect_b64 s[8:9], -1, 0
	s_and_b64 vcc, s[8:9], exec
	s_cselect_b32 s8, s10, s74
	v_lshl_or_b32 v2, s8, 6, v194
	s_mov_b64 s[10:11], -1
	s_cbranch_vccnz .LBB0_749
	v_lshrrev_b32_e32 v4, s74, v196
	v_and_b32_e32 v4, 1, v4
	v_mov_b64_e32 v[82:83], v[114:115]
	v_mov_b64_e32 v[98:99], v[130:131]
	v_cmp_eq_u32_e64 s[8:9], 1, v4
	s_cmp_lg_u32 s69, s74
	v_mov_b64_e32 v[84:85], v[116:117]
	v_mov_b64_e32 v[86:87], v[118:119]
	v_mov_b64_e32 v[88:89], v[120:121]
	v_mov_b64_e32 v[90:91], v[122:123]
	v_mov_b64_e32 v[92:93], v[124:125]
	v_mov_b64_e32 v[94:95], v[126:127]
	v_mov_b64_e32 v[96:97], v[128:129]
	v_mov_b64_e32 v[100:101], v[132:133]
	v_mov_b64_e32 v[102:103], v[134:135]
	v_mov_b64_e32 v[104:105], v[136:137]
	v_mov_b64_e32 v[106:107], v[138:139]
	v_mov_b64_e32 v[108:109], v[140:141]
	v_mov_b64_e32 v[110:111], v[142:143]
	v_mov_b64_e32 v[112:113], v[144:145]
	s_cbranch_scc1 .LBB0_748
	v_cmp_le_i32_e32 vcc, v2, v190
	v_or_b32_e32 v4, 32, v2
	s_nop 0
	v_cndmask_b32_e32 v98, v186, v130, vcc
	v_cmp_le_i32_e32 vcc, v4, v190
	v_or_b32_e32 v4, 33, v2
	s_nop 0
	v_cndmask_b32_e32 v82, v186, v114, vcc
	v_cmp_lt_i32_e32 vcc, v2, v190
	s_nop 1
	v_cndmask_b32_e32 v99, v186, v131, vcc
	v_cmp_le_i32_e32 vcc, v4, v190
	v_or_b32_e32 v4, 2, v2
	s_nop 0
	v_cndmask_b32_e32 v83, v186, v115, vcc
	v_cmp_le_i32_e32 vcc, v4, v190
	v_or_b32_e32 v4, 34, v2
	s_nop 0
	v_cndmask_b32_e32 v100, v186, v132, vcc
	v_cmp_le_i32_e32 vcc, v4, v190
	v_or_b32_e32 v4, 3, v2
	s_nop 0
	v_cndmask_b32_e32 v84, v186, v116, vcc
	v_cmp_le_i32_e32 vcc, v4, v190
	v_or_b32_e32 v4, 35, v2
	s_nop 0
	v_cndmask_b32_e32 v101, v186, v133, vcc
	v_cmp_le_i32_e32 vcc, v4, v190
	v_or_b32_e32 v4, 8, v2
	s_nop 0
	v_cndmask_b32_e32 v85, v186, v117, vcc
	v_cmp_le_i32_e32 vcc, v4, v190
	v_or_b32_e32 v4, 40, v2
	s_nop 0
	v_cndmask_b32_e32 v102, v186, v134, vcc
	v_cmp_le_i32_e32 vcc, v4, v190
	v_or_b32_e32 v4, 9, v2
	s_nop 0
	v_cndmask_b32_e32 v86, v186, v118, vcc
	v_cmp_le_i32_e32 vcc, v4, v190
	v_or_b32_e32 v4, 41, v2
	s_nop 0
	v_cndmask_b32_e32 v103, v186, v135, vcc
	v_cmp_le_i32_e32 vcc, v4, v190
	v_or_b32_e32 v4, 10, v2
	s_nop 0
	v_cndmask_b32_e32 v87, v186, v119, vcc
	v_cmp_le_i32_e32 vcc, v4, v190
	v_or_b32_e32 v4, 42, v2
	s_nop 0
	v_cndmask_b32_e32 v104, v186, v136, vcc
	v_cmp_le_i32_e32 vcc, v4, v190
	v_or_b32_e32 v4, 11, v2
	s_nop 0
	v_cndmask_b32_e32 v88, v186, v120, vcc
	v_cmp_le_i32_e32 vcc, v4, v190
	v_or_b32_e32 v4, 43, v2
	s_nop 0
	v_cndmask_b32_e32 v105, v186, v137, vcc
	v_cmp_le_i32_e32 vcc, v4, v190
	v_or_b32_e32 v4, 16, v2
	s_nop 0
	v_cndmask_b32_e32 v89, v186, v121, vcc
	v_cmp_le_i32_e32 vcc, v4, v190
	v_or_b32_e32 v4, 48, v2
	s_nop 0
	v_cndmask_b32_e32 v106, v186, v138, vcc
	v_cmp_le_i32_e32 vcc, v4, v190
	v_or_b32_e32 v4, 17, v2
	s_nop 0
	v_cndmask_b32_e32 v90, v186, v122, vcc
	v_cmp_le_i32_e32 vcc, v4, v190
	v_or_b32_e32 v4, 49, v2
	s_nop 0
	v_cndmask_b32_e32 v107, v186, v139, vcc
	v_cmp_le_i32_e32 vcc, v4, v190
	v_or_b32_e32 v4, 18, v2
	s_nop 0
	v_cndmask_b32_e32 v91, v186, v123, vcc
	v_cmp_le_i32_e32 vcc, v4, v190
	v_or_b32_e32 v4, 50, v2
	s_nop 0
	v_cndmask_b32_e32 v108, v186, v140, vcc
	v_cmp_le_i32_e32 vcc, v4, v190
	v_or_b32_e32 v4, 19, v2
	s_nop 0
	v_cndmask_b32_e32 v92, v186, v124, vcc
	v_cmp_le_i32_e32 vcc, v4, v190
	v_or_b32_e32 v4, 51, v2
	s_nop 0
	v_cndmask_b32_e32 v109, v186, v141, vcc
	v_cmp_le_i32_e32 vcc, v4, v190
	v_or_b32_e32 v4, 24, v2
	s_nop 0
	v_cndmask_b32_e32 v93, v186, v125, vcc
	v_cmp_le_i32_e32 vcc, v4, v190
	v_or_b32_e32 v4, 56, v2
	s_nop 0
	v_cndmask_b32_e32 v110, v186, v142, vcc
	v_cmp_le_i32_e32 vcc, v4, v190
	v_or_b32_e32 v4, 25, v2
	s_nop 0
	v_cndmask_b32_e32 v94, v186, v126, vcc
	v_cmp_le_i32_e32 vcc, v4, v190
	v_or_b32_e32 v4, 57, v2
	s_nop 0
	v_cndmask_b32_e32 v111, v186, v143, vcc
	v_cmp_le_i32_e32 vcc, v4, v190
	v_or_b32_e32 v4, 26, v2
	s_nop 0
	v_cndmask_b32_e32 v95, v186, v127, vcc
	v_cmp_le_i32_e32 vcc, v4, v190
	v_or_b32_e32 v4, 58, v2
	s_nop 0
	v_cndmask_b32_e32 v112, v186, v144, vcc
	v_cmp_le_i32_e32 vcc, v4, v190
	v_or_b32_e32 v4, 27, v2
	s_nop 0
	v_cndmask_b32_e32 v96, v186, v128, vcc
	v_cmp_le_i32_e32 vcc, v4, v190
	v_or_b32_e32 v4, 59, v2
	s_nop 0
	v_cndmask_b32_e32 v113, v186, v145, vcc
	v_cmp_le_i32_e32 vcc, v4, v190
	s_nop 1
	v_cndmask_b32_e32 v97, v186, v129, vcc

; #define LAS __attribute__((address_space(3)))
; #define MFMA32(a, b, c) __builtin_amdgcn_mfma_f32_32x32x16_bf16((a), (b), (c), 0, 0, 0)
; DI float fexp2(float x) { return __builtin_amdgcn_exp2f(x); }
; DI s16x4 vtr(const LAS unsigned char* p) { return __builtin_bit_cast(s16x4, __builtin_amdgcn_ds_read_tr16_b64_v4i16((LAS v4i16_t*)p)); }
; DI void flash_qk(const LAS unsigned char* kb, const bf16x8 (&qf)[4], f32x16& p0, f32x16& p1, int r32, int h) {
;     ...
;     for (int s = 0; s < 4; ++s) {
;         const int off = r32 * 128 + (((2 * s + h) ^ sw) << 4);
;         const bf16x8 a0 = *(const LAS bf16x8*)(kb + off), a1 = *(const LAS bf16x8*)(kb + off + 4096);
;         p0 = MFMA32(a0, qf[s], p0); p1 = MFMA32(a1, qf[s], p1);
;     }
; DI void flash_pv(FState& st, f32x16& p0, f32x16& p1, bool rowon, const LAS unsigned char* vb, int lane) {
;     ...
;     const float cl = rowon ? SM_C : 0.0f;
;     const float bl = rowon ? ((st.m == NINF) ? 0.0f : -st.m * SM_C) : NINF;
;     float sum = 0.f;
; #pragma unroll
;     for (int r = 0; r < 16; ++r) { p0[r] = fexp2(__builtin_fmaf(p0[r], cl, bl)); p1[r] = fexp2(__builtin_fmaf(p1[r], cl, bl)); sum += p0[r] + p1[r]; }
;     st.l += sum;
;     const int h = lane >> 5;
;     const int vx = (((lane & 15) >> 3) & 1) * 64;
;     const LAS unsigned char* vp = vb + (4 * h + ((lane & 15) >> 2)) * 128 + ((lane >> 4) & 1) * 32 + (lane & 3) * 8;
; #pragma unroll
;     for (int sub = 0; sub < 2; ++sub)
; #pragma unroll
;         for (int s2 = 0; s2 < 2; ++s2) {
;             const bf16x8 pf = pack8h(sub ? p1 : p0, s2);
;             const LAS unsigned char* vq = vp + (32 * sub + 16 * s2) * 128;
;             { const s16x4 lo = vtr(vq + vx), hi = vtr(vq + 1024 + vx); const bf16x8 vf = {lo[0], lo[1], lo[2], lo[3], hi[0], hi[1], hi[2], hi[3]}; st.o0 = MFMA32(vf, pf, st.o0); }
;             { const s16x4 lo = vtr(vq + (64 - vx)), hi = vtr(vq + 1024 + (64 - vx)); const bf16x8 vf = {lo[0], lo[1], lo[2], lo[3], hi[0], hi[1], hi[2], hi[3]}; st.o1 = MFMA32(vf, pf, st.o1); }
.LBB0_759:
	s_or_b64 exec, exec, s[4:5]
	ds_read_b128 v[226:229], v221 offset:16384
	ds_read_b128 v[230:233], v221 offset:20480
	ds_read_b128 v[234:237], v222 offset:16384
	ds_read_b128 v[238:241], v222 offset:20480
	v_fma_f32 v2, v98, v5, v4
	v_exp_f32_e32 v12, v2
	v_fma_f32 v2, v82, v5, v4
	v_exp_f32_e32 v246, v2
	v_fma_f32 v2, v99, v5, v4
	v_exp_f32_e32 v6, v2
	s_waitcnt lgkmcnt(3)
	v_mfma_f32_32x32x16_bf16 v[130:145], v[226:229], v[146:149], 0
	v_fma_f32 v2, v83, v5, v4
	v_exp_f32_e32 v2, v2
	v_add_f32_e32 v7, v12, v246
	s_add_i32 s77, s74, 1
	s_cmp_ge_u32 s77, s51
	v_pk_add_f32 v[8:9], v[6:7], v[2:3]
	s_waitcnt lgkmcnt(2)
	v_mfma_f32_32x32x16_bf16 v[114:129], v[230:233], v[146:149], 0
	ds_read_b128 v[226:229], v223 offset:16384
	ds_read_b128 v[230:233], v223 offset:20480
	v_fma_f32 v7, v100, v5, v4
	v_pk_add_f32 v[98:99], v[8:9], v[8:9] op_sel_hi:[0,1]
	v_fma_f32 v8, v84, v5, v4
	v_exp_f32_e32 v7, v7
	v_exp_f32_e32 v247, v8
	v_fma_f32 v8, v101, v5, v4
	v_fma_f32 v9, v85, v5, v4
	v_exp_f32_e32 v8, v8
	s_waitcnt lgkmcnt(3)
	v_mfma_f32_32x32x16_bf16 v[130:145], v[234:237], v[150:153], v[130:145]
	v_exp_f32_e32 v98, v9
	v_add_f32_e32 v9, v7, v247
	v_cvt_pk_bf16_f32 v6, v12, v6
	v_cvt_pk_bf16_f32 v7, v7, v8
	v_pk_add_f32 v[10:11], v[8:9], v[98:99]
	v_fma_f32 v9, v102, v5, v4
	v_pk_add_f32 v[100:101], v[10:11], v[10:11] op_sel_hi:[0,1]
	v_fma_f32 v10, v86, v5, v4
	s_waitcnt lgkmcnt(2)
	v_mfma_f32_32x32x16_bf16 v[114:129], v[238:241], v[150:153], v[114:129]
	ds_read_b128 v[234:237], v224 offset:16384
	ds_read_b128 v[238:241], v224 offset:20480
	v_exp_f32_e32 v99, v10
	v_fma_f32 v10, v103, v5, v4
	v_exp_f32_e32 v9, v9
	v_exp_f32_e32 v14, v10
	v_fma_f32 v10, v87, v5, v4
	v_exp_f32_e32 v100, v10
	v_add_f32_e32 v15, v9, v99
	v_cvt_pk_bf16_f32 v8, v9, v14
	s_waitcnt lgkmcnt(3)
	v_mfma_f32_32x32x16_bf16 v[130:145], v[226:229], v[154:157], v[130:145]
	v_pk_add_f32 v[10:11], v[14:15], v[100:101]
	s_nop 0
	v_pk_add_f32 v[86:87], v[10:11], v[10:11] op_sel_hi:[0,1]
	v_fma_f32 v10, v104, v5, v4
	v_exp_f32_e32 v15, v10
	v_fma_f32 v10, v88, v5, v4
	v_exp_f32_e32 v101, v10
	v_fma_f32 v10, v105, v5, v4
	s_waitcnt lgkmcnt(2)
	v_mfma_f32_32x32x16_bf16 v[114:129], v[230:233], v[154:157], v[114:129]
	v_exp_f32_e32 v16, v10
	v_fma_f32 v10, v89, v5, v4
	v_exp_f32_e32 v86, v10
	v_add_f32_e32 v17, v15, v101
	v_cvt_pk_bf16_f32 v9, v15, v16
	v_pk_add_f32 v[10:11], v[16:17], v[86:87]
	s_nop 0
	v_pk_add_f32 v[88:89], v[10:11], v[10:11] op_sel_hi:[0,1]
	s_waitcnt lgkmcnt(1)
	v_mfma_f32_32x32x16_bf16 v[130:145], v[234:237], v[158:161], v[130:145]
	v_fma_f32 v10, v106, v5, v4
	v_exp_f32_e32 v87, v10
	v_fma_f32 v10, v90, v5, v4
	v_exp_f32_e32 v248, v10
	v_fma_f32 v10, v107, v5, v4
	v_exp_f32_e32 v90, v10
	v_fma_f32 v10, v91, v5, v4
	v_exp_f32_e32 v88, v10
	s_waitcnt lgkmcnt(0)
	v_mfma_f32_32x32x16_bf16 v[114:129], v[238:241], v[158:161], v[114:129]
	v_fma_f32 v10, v108, v5, v4
	v_exp_f32_e32 v107, v10
	v_fma_f32 v10, v92, v5, v4
	v_add_f32_e32 v91, v87, v248
	v_exp_f32_e32 v108, v10
	v_pk_add_f32 v[10:11], v[90:91], v[88:89]
	v_fma_f32 v91, v112, v5, v4
	v_pk_add_f32 v[102:103], v[10:11], v[10:11] op_sel_hi:[0,1]
	v_fma_f32 v10, v109, v5, v4
	v_exp_f32_e32 v104, v10
	v_fma_f32 v10, v93, v5, v4
	v_exp_f32_e32 v102, v10
	v_add_u32_e32 v10, s76, v211
	v_add3_u32 v17, v10, v203, v204
	v_add_u32_e32 v218, v17, v202
	ds_read_b64_tr_b16 v[10:11], v218 offset:8192
	ds_read_b64_tr_b16 v[12:13], v218 offset:9216
	v_add_u32_e32 v217, v17, v213
	ds_read_b64_tr_b16 v[14:15], v217 offset:8256
	ds_read_b64_tr_b16 v[16:17], v217 offset:9280
	ds_read_b64_tr_b16 v[82:83], v218 offset:10240
	ds_read_b64_tr_b16 v[84:85], v218 offset:11264
	s_waitcnt lgkmcnt(4)
	v_mfma_f32_32x32x16_bf16 v[66:81], v[10:13], v[6:9], v[66:81]
	v_fma_f32 v10, v110, v5, v4
	v_exp_f32_e32 v89, v10
	v_fma_f32 v10, v111, v5, v4
	v_exp_f32_e32 v92, v10
	v_exp_f32_e32 v109, v91
	v_add_f32_e32 v105, v107, v108
	ds_read_b64_tr_b16 v[10:11], v217 offset:10304
	ds_read_b64_tr_b16 v[12:13], v217 offset:11328
	s_waitcnt lgkmcnt(4)
	v_mfma_f32_32x32x16_bf16 v[50:65], v[14:17], v[6:9], v[50:65]
	v_fma_f32 v6, v113, v5, v4
	v_exp_f32_e32 v106, v6
	v_cvt_pk_bf16_f32 v6, v87, v90
	v_cvt_pk_bf16_f32 v7, v107, v104
	v_cvt_pk_bf16_f32 v8, v89, v92
	v_cvt_pk_bf16_f32 v9, v109, v106
	v_pk_add_f32 v[14:15], v[104:105], v[102:103]
	s_waitcnt lgkmcnt(2)
	v_mfma_f32_32x32x16_bf16 v[66:81], v[82:85], v[6:9], v[66:81]
	v_add_f32_e64 v90, v14, v14
	v_add_f32_e64 v91, v14, v15
	v_fma_f32 v14, v94, v5, v4
	v_exp_f32_e32 v94, v14
	ds_read_b64_tr_b16 v[14:15], v218 offset:12288
	ds_read_b64_tr_b16 v[16:17], v218 offset:13312
	v_fma_f32 v82, v95, v5, v4
	v_exp_f32_e32 v90, v82
	v_add_f32_e32 v93, v89, v94
	s_waitcnt lgkmcnt(2)
	v_mfma_f32_32x32x16_bf16 v[50:65], v[10:13], v[6:9], v[50:65]
	v_cvt_pk_bf16_f32 v6, v246, v2
	v_cvt_pk_bf16_f32 v7, v247, v98
	v_cvt_pk_bf16_f32 v8, v99, v100
	v_cvt_pk_bf16_f32 v9, v101, v86
	ds_read_b64_tr_b16 v[10:11], v218 offset:14336
	ds_read_b64_tr_b16 v[12:13], v218 offset:15360
	v_pk_add_f32 v[82:83], v[92:93], v[90:91]
	v_fma_f32 v2, v96, v5, v4
	s_waitcnt lgkmcnt(2)
	v_mfma_f32_32x32x16_bf16 v[66:81], v[14:17], v[6:9], v[66:81]
	ds_read_b64_tr_b16 v[14:15], v217 offset:12352
	ds_read_b64_tr_b16 v[16:17], v217 offset:13376
	v_add_f32_e64 v86, v82, v82
	v_add_f32_e64 v87, v82, v83
	v_fmac_f32_e32 v4, v97, v5
	ds_read_b64_tr_b16 v[82:83], v217 offset:14400
	ds_read_b64_tr_b16 v[84:85], v217 offset:15424
	v_exp_f32_e32 v2, v2
	v_exp_f32_e32 v86, v4
	v_cvt_pk_bf16_f32 v4, v248, v88
	s_waitcnt lgkmcnt(2)
	v_mfma_f32_32x32x16_bf16 v[50:65], v[14:17], v[6:9], v[50:65]
	v_cvt_pk_bf16_f32 v5, v108, v102
	v_cvt_pk_bf16_f32 v6, v94, v90
	v_cvt_pk_bf16_f32 v7, v2, v86
	v_add_f32_e32 v107, v109, v2
	v_add_f32_e64 v8, v106, v86
	v_add_f32_e64 v9, v107, v87
	v_add_f32_e32 v2, v8, v9
	v_mfma_f32_32x32x16_bf16 v[66:81], v[10:13], v[4:7], v[66:81]
	v_add_f32_e32 v214, v214, v2
	s_waitcnt lgkmcnt(0)
	v_mfma_f32_32x32x16_bf16 v[50:65], v[82:85], v[4:7], v[50:65]
	s_cbranch_scc1 .LBB0_780
	s_movk_i32 s76, 0x4000
	s_add_i32 s4, s74, 5
	s_cmp_ge_u32 s4, s51
	s_waitcnt vmcnt(1)
	ds_write_b128 v205, v[182:185] offset:32768
	s_waitcnt vmcnt(0)
	ds_write_b128 v212, v[178:181] offset:40960
	s_waitcnt lgkmcnt(0)
	s_barrier
	s_cbranch_scc1 .LBB0_762
	s_cmp_gt_u32 s4, s69
	s_cselect_b64 s[8:9], -1, 0
	s_mov_b32 s5, s52
	s_and_b64 s[8:9], s[8:9], exec
	s_cselect_b32 s4, s5, s4
	s_cselect_b32 s16, 0x1000, s65
	s_cselect_b32 s8, s64, 0x500
	s_lshl_b32 s4, s4, 6
	s_mov_b32 s9, s17
	v_mad_i64_i32 v[4:5], s[4:5], s4, v199, v[192:193]
	v_lshl_add_u64 v[6:7], v[4:5], 0, s[8:9]
	v_lshl_add_u64 v[4:5], v[4:5], 0, s[16:17]
	global_load_dwordx4 v[182:185], v[6:7], off
	global_load_dwordx4 v[178:181], v[4:5], off

.LBB0_764:
	s_add_i32 s8, s52, 4
	s_cmp_lt_u32 s74, s69
	s_cselect_b32 s8, s77, s8
	s_cmp_ge_u32 s74, s69
	s_mov_b64 s[10:11], -1
	v_lshl_or_b32 v2, s8, 6, v194
	s_mov_b64 s[8:9], -1
	s_cbranch_scc0 .LBB0_768
	s_cmp_eq_u32 s75, 8
	s_cselect_b64 s[10:11], -1, 0
	s_or_b64 s[4:5], s[4:5], s[10:11]
	v_mov_b64_e32 v[82:83], v[114:115]
	v_mov_b64_e32 v[98:99], v[130:131]
	s_andn2_b64 vcc, exec, s[4:5]
	v_mov_b64_e32 v[84:85], v[116:117]
	v_mov_b64_e32 v[86:87], v[118:119]
	v_mov_b64_e32 v[88:89], v[120:121]
	v_mov_b64_e32 v[90:91], v[122:123]
	v_mov_b64_e32 v[92:93], v[124:125]
	v_mov_b64_e32 v[94:95], v[126:127]
	v_mov_b64_e32 v[96:97], v[128:129]
	v_mov_b64_e32 v[100:101], v[132:133]
	v_mov_b64_e32 v[102:103], v[134:135]
	v_mov_b64_e32 v[104:105], v[136:137]
	v_mov_b64_e32 v[106:107], v[138:139]
	v_mov_b64_e32 v[108:109], v[140:141]
	v_mov_b64_e32 v[110:111], v[142:143]
	v_mov_b64_e32 v[112:113], v[144:145]
	s_cbranch_vccnz .LBB0_767
	v_cmp_le_i32_e32 vcc, v2, v190
	v_cmp_gt_i32_e64 s[4:5], v2, v210
	s_and_b64 vcc, vcc, s[4:5]
	v_or_b32_e32 v4, 32, v2
	v_cndmask_b32_e32 v98, v186, v130, vcc
	v_cmp_le_i32_e32 vcc, v4, v190
	v_cmp_gt_i32_e64 s[4:5], v4, v210
	s_and_b64 vcc, vcc, s[4:5]
	v_cndmask_b32_e32 v82, v186, v114, vcc
	v_cmp_lt_i32_e32 vcc, v2, v190
	v_cmp_ge_i32_e64 s[4:5], v2, v210
	s_and_b64 vcc, vcc, s[4:5]
	v_or_b32_e32 v4, 33, v2
	v_cndmask_b32_e32 v99, v186, v131, vcc
	v_cmp_le_i32_e32 vcc, v4, v190
	v_cmp_gt_i32_e64 s[4:5], v4, v210
	s_and_b64 vcc, vcc, s[4:5]
	v_or_b32_e32 v4, 2, v2
	v_cndmask_b32_e32 v83, v186, v115, vcc
	v_cmp_le_i32_e32 vcc, v4, v190
	v_cmp_gt_i32_e64 s[4:5], v4, v210
	s_and_b64 vcc, vcc, s[4:5]
	v_or_b32_e32 v4, 34, v2
	v_cndmask_b32_e32 v100, v186, v132, vcc
	v_cmp_le_i32_e32 vcc, v4, v190
	v_cmp_gt_i32_e64 s[4:5], v4, v210
	s_and_b64 vcc, vcc, s[4:5]
	v_or_b32_e32 v4, 3, v2
	v_cndmask_b32_e32 v84, v186, v116, vcc
	v_cmp_le_i32_e32 vcc, v4, v190
	v_cmp_gt_i32_e64 s[4:5], v4, v210
	s_and_b64 vcc, vcc, s[4:5]
	v_or_b32_e32 v4, 35, v2
	v_cndmask_b32_e32 v101, v186, v133, vcc
	v_cmp_le_i32_e32 vcc, v4, v190
	v_cmp_gt_i32_e64 s[4:5], v4, v210
	s_and_b64 vcc, vcc, s[4:5]
	v_or_b32_e32 v4, 8, v2
	v_cndmask_b32_e32 v85, v186, v117, vcc
	v_cmp_le_i32_e32 vcc, v4, v190
	v_cmp_gt_i32_e64 s[4:5], v4, v210
	s_and_b64 vcc, vcc, s[4:5]
	v_or_b32_e32 v4, 40, v2
	v_cndmask_b32_e32 v102, v186, v134, vcc
	v_cmp_le_i32_e32 vcc, v4, v190
	v_cmp_gt_i32_e64 s[4:5], v4, v210
	s_and_b64 vcc, vcc, s[4:5]
	v_or_b32_e32 v4, 9, v2
	v_cndmask_b32_e32 v86, v186, v118, vcc
	v_cmp_le_i32_e32 vcc, v4, v190
	v_cmp_gt_i32_e64 s[4:5], v4, v210
	s_and_b64 vcc, vcc, s[4:5]
	v_or_b32_e32 v4, 41, v2
	v_cndmask_b32_e32 v103, v186, v135, vcc
	v_cmp_le_i32_e32 vcc, v4, v190
	v_cmp_gt_i32_e64 s[4:5], v4, v210
	s_and_b64 vcc, vcc, s[4:5]
	v_or_b32_e32 v4, 10, v2
	v_cndmask_b32_e32 v87, v186, v119, vcc
	v_cmp_le_i32_e32 vcc, v4, v190
	v_cmp_gt_i32_e64 s[4:5], v4, v210
	s_and_b64 vcc, vcc, s[4:5]
	v_or_b32_e32 v4, 42, v2
	v_cndmask_b32_e32 v104, v186, v136, vcc
	v_cmp_le_i32_e32 vcc, v4, v190
	v_cmp_gt_i32_e64 s[4:5], v4, v210
	s_and_b64 vcc, vcc, s[4:5]
	v_or_b32_e32 v4, 11, v2
	v_cndmask_b32_e32 v88, v186, v120, vcc
	v_cmp_le_i32_e32 vcc, v4, v190
	v_cmp_gt_i32_e64 s[4:5], v4, v210
	s_and_b64 vcc, vcc, s[4:5]
	v_or_b32_e32 v4, 43, v2
	v_cndmask_b32_e32 v105, v186, v137, vcc
	v_cmp_le_i32_e32 vcc, v4, v190
	v_cmp_gt_i32_e64 s[4:5], v4, v210
	s_and_b64 vcc, vcc, s[4:5]
	v_or_b32_e32 v4, 16, v2
	v_cndmask_b32_e32 v89, v186, v121, vcc
	v_cmp_le_i32_e32 vcc, v4, v190
	v_cmp_gt_i32_e64 s[4:5], v4, v210
	s_and_b64 vcc, vcc, s[4:5]
	v_or_b32_e32 v4, 48, v2
	v_cndmask_b32_e32 v106, v186, v138, vcc
	v_cmp_le_i32_e32 vcc, v4, v190
	v_cmp_gt_i32_e64 s[4:5], v4, v210
	s_and_b64 vcc, vcc, s[4:5]
	v_or_b32_e32 v4, 17, v2
	v_cndmask_b32_e32 v90, v186, v122, vcc
	v_cmp_le_i32_e32 vcc, v4, v190
	v_cmp_gt_i32_e64 s[4:5], v4, v210
	s_and_b64 vcc, vcc, s[4:5]
	v_or_b32_e32 v4, 49, v2
	v_cndmask_b32_e32 v107, v186, v139, vcc
	v_cmp_le_i32_e32 vcc, v4, v190
	v_cmp_gt_i32_e64 s[4:5], v4, v210
	s_and_b64 vcc, vcc, s[4:5]
	v_or_b32_e32 v4, 18, v2
	v_cndmask_b32_e32 v91, v186, v123, vcc
	v_cmp_le_i32_e32 vcc, v4, v190
	v_cmp_gt_i32_e64 s[4:5], v4, v210
	s_and_b64 vcc, vcc, s[4:5]
	v_or_b32_e32 v4, 50, v2
	v_cndmask_b32_e32 v108, v186, v140, vcc
	v_cmp_le_i32_e32 vcc, v4, v190
	v_cmp_gt_i32_e64 s[4:5], v4, v210
	s_and_b64 vcc, vcc, s[4:5]
	v_or_b32_e32 v4, 19, v2
	v_cndmask_b32_e32 v92, v186, v124, vcc
	v_cmp_le_i32_e32 vcc, v4, v190
	v_cmp_gt_i32_e64 s[4:5], v4, v210
	s_and_b64 vcc, vcc, s[4:5]
	v_or_b32_e32 v4, 51, v2
	v_cndmask_b32_e32 v109, v186, v141, vcc
	v_cmp_le_i32_e32 vcc, v4, v190
	v_cmp_gt_i32_e64 s[4:5], v4, v210
	s_and_b64 vcc, vcc, s[4:5]
	v_or_b32_e32 v4, 24, v2
	v_cndmask_b32_e32 v93, v186, v125, vcc
	v_cmp_le_i32_e32 vcc, v4, v190
	v_cmp_gt_i32_e64 s[4:5], v4, v210
	s_and_b64 vcc, vcc, s[4:5]
	v_or_b32_e32 v4, 56, v2
	v_cndmask_b32_e32 v110, v186, v142, vcc
	v_cmp_le_i32_e32 vcc, v4, v190
	v_cmp_gt_i32_e64 s[4:5], v4, v210
	s_and_b64 vcc, vcc, s[4:5]
	v_or_b32_e32 v4, 25, v2
	v_cndmask_b32_e32 v94, v186, v126, vcc
	v_cmp_le_i32_e32 vcc, v4, v190
	v_cmp_gt_i32_e64 s[4:5], v4, v210
	s_and_b64 vcc, vcc, s[4:5]
	v_or_b32_e32 v4, 57, v2
	v_cndmask_b32_e32 v111, v186, v143, vcc
	v_cmp_le_i32_e32 vcc, v4, v190
	v_cmp_gt_i32_e64 s[4:5], v4, v210
	s_and_b64 vcc, vcc, s[4:5]
	v_or_b32_e32 v4, 26, v2
	v_cndmask_b32_e32 v95, v186, v127, vcc
	v_cmp_le_i32_e32 vcc, v4, v190
	v_cmp_gt_i32_e64 s[4:5], v4, v210
	s_and_b64 vcc, vcc, s[4:5]
	v_or_b32_e32 v4, 58, v2
	v_cndmask_b32_e32 v112, v186, v144, vcc
	v_cmp_le_i32_e32 vcc, v4, v190
	v_cmp_gt_i32_e64 s[4:5], v4, v210
	s_and_b64 vcc, vcc, s[4:5]
	v_or_b32_e32 v4, 27, v2
	v_cndmask_b32_e32 v96, v186, v128, vcc
	v_cmp_le_i32_e32 vcc, v4, v190
	v_cmp_gt_i32_e64 s[4:5], v4, v210
	s_and_b64 vcc, vcc, s[4:5]
	v_or_b32_e32 v4, 59, v2
	v_cndmask_b32_e32 v113, v186, v145, vcc
	v_cmp_le_i32_e32 vcc, v4, v190
	v_cmp_gt_i32_e64 s[4:5], v4, v210
	s_and_b64 vcc, vcc, s[4:5]
	v_cndmask_b32_e32 v97, v186, v129, vcc

; #define LAS __attribute__((address_space(3)))
; #define MFMA32(a, b, c) __builtin_amdgcn_mfma_f32_32x32x16_bf16((a), (b), (c), 0, 0, 0)
; DI float fexp2(float x) { return __builtin_amdgcn_exp2f(x); }
; DI s16x4 vtr(const LAS unsigned char* p) { return __builtin_bit_cast(s16x4, __builtin_amdgcn_ds_read_tr16_b64_v4i16((LAS v4i16_t*)p)); }
; DI void flash_qk(const LAS unsigned char* kb, const bf16x8 (&qf)[4], f32x16& p0, f32x16& p1, int r32, int h) {
;     ...
;     for (int s = 0; s < 4; ++s) {
;         const int off = r32 * 128 + (((2 * s + h) ^ sw) << 4);
;         const bf16x8 a0 = *(const LAS bf16x8*)(kb + off), a1 = *(const LAS bf16x8*)(kb + off + 4096);
;         p0 = MFMA32(a0, qf[s], p0); p1 = MFMA32(a1, qf[s], p1);
;     }
; DI void flash_pv(FState& st, f32x16& p0, f32x16& p1, bool rowon, const LAS unsigned char* vb, int lane) {
;     ...
;     const float cl = rowon ? SM_C : 0.0f;
;     const float bl = rowon ? ((st.m == NINF) ? 0.0f : -st.m * SM_C) : NINF;
;     float sum = 0.f;
; #pragma unroll
;     for (int r = 0; r < 16; ++r) { p0[r] = fexp2(__builtin_fmaf(p0[r], cl, bl)); p1[r] = fexp2(__builtin_fmaf(p1[r], cl, bl)); sum += p0[r] + p1[r]; }
;     st.l += sum;
;     const int h = lane >> 5;
;     const int vx = (((lane & 15) >> 3) & 1) * 64;
;     const LAS unsigned char* vp = vb + (4 * h + ((lane & 15) >> 2)) * 128 + ((lane >> 4) & 1) * 32 + (lane & 3) * 8;
; #pragma unroll
;     for (int sub = 0; sub < 2; ++sub)
; #pragma unroll
;         for (int s2 = 0; s2 < 2; ++s2) {
;             const bf16x8 pf = pack8h(sub ? p1 : p0, s2);
;             const LAS unsigned char* vq = vp + (32 * sub + 16 * s2) * 128;
;             { const s16x4 lo = vtr(vq + vx), hi = vtr(vq + 1024 + vx); const bf16x8 vf = {lo[0], lo[1], lo[2], lo[3], hi[0], hi[1], hi[2], hi[3]}; st.o0 = MFMA32(vf, pf, st.o0); }
;             { const s16x4 lo = vtr(vq + (64 - vx)), hi = vtr(vq + 1024 + (64 - vx)); const bf16x8 vf = {lo[0], lo[1], lo[2], lo[3], hi[0], hi[1], hi[2], hi[3]}; st.o1 = MFMA32(vf, pf, st.o1); }
.LBB0_778:
	s_or_b64 exec, exec, s[4:5]
	ds_read_b128 v[226:229], v221 offset:32768
	ds_read_b128 v[230:233], v221 offset:36864
	ds_read_b128 v[234:237], v222 offset:32768
	ds_read_b128 v[238:241], v222 offset:36864
	v_fma_f32 v2, v98, v5, v4
	v_exp_f32_e32 v12, v2
	v_fma_f32 v2, v82, v5, v4
	v_exp_f32_e32 v246, v2
	v_fma_f32 v2, v99, v5, v4
	v_exp_f32_e32 v6, v2
	s_waitcnt lgkmcnt(3)
	v_mfma_f32_32x32x16_bf16 v[130:145], v[226:229], v[146:149], 0
	v_fma_f32 v2, v83, v5, v4
	v_exp_f32_e32 v2, v2
	v_add_f32_e32 v7, v12, v246
	v_pk_add_f32 v[8:9], v[6:7], v[2:3]
	s_nop 0
	v_pk_add_f32 v[98:99], v[8:9], v[8:9] op_sel_hi:[0,1]
	s_waitcnt lgkmcnt(2)
	v_mfma_f32_32x32x16_bf16 v[114:129], v[230:233], v[146:149], 0
	ds_read_b128 v[226:229], v223 offset:32768
	ds_read_b128 v[230:233], v223 offset:36864
	v_fma_f32 v7, v100, v5, v4
	v_fma_f32 v8, v84, v5, v4
	v_exp_f32_e32 v7, v7
	v_exp_f32_e32 v247, v8
	v_fma_f32 v8, v101, v5, v4
	v_fma_f32 v9, v85, v5, v4
	v_exp_f32_e32 v8, v8
	v_exp_f32_e32 v98, v9
	s_waitcnt lgkmcnt(3)
	v_mfma_f32_32x32x16_bf16 v[130:145], v[234:237], v[150:153], v[130:145]
	v_add_f32_e32 v9, v7, v247
	v_cvt_pk_bf16_f32 v6, v12, v6
	v_cvt_pk_bf16_f32 v7, v7, v8
	v_pk_add_f32 v[10:11], v[8:9], v[98:99]
	v_fma_f32 v9, v102, v5, v4
	v_pk_add_f32 v[100:101], v[10:11], v[10:11] op_sel_hi:[0,1]
	v_fma_f32 v10, v86, v5, v4
	v_exp_f32_e32 v99, v10
	s_waitcnt lgkmcnt(2)
	v_mfma_f32_32x32x16_bf16 v[114:129], v[238:241], v[150:153], v[114:129]
	ds_read_b128 v[234:237], v224 offset:32768
	ds_read_b128 v[238:241], v224 offset:36864
	v_fma_f32 v10, v103, v5, v4
	v_exp_f32_e32 v9, v9
	v_exp_f32_e32 v14, v10
	v_fma_f32 v10, v87, v5, v4
	v_exp_f32_e32 v100, v10
	v_add_f32_e32 v15, v9, v99
	v_cvt_pk_bf16_f32 v8, v9, v14
	v_pk_add_f32 v[10:11], v[14:15], v[100:101]
	s_waitcnt lgkmcnt(3)
	v_mfma_f32_32x32x16_bf16 v[130:145], v[226:229], v[154:157], v[130:145]
	s_nop 0
	v_pk_add_f32 v[86:87], v[10:11], v[10:11] op_sel_hi:[0,1]
	v_fma_f32 v10, v104, v5, v4
	v_exp_f32_e32 v15, v10
	v_fma_f32 v10, v88, v5, v4
	v_exp_f32_e32 v101, v10
	v_fma_f32 v10, v105, v5, v4
	v_exp_f32_e32 v16, v10
	s_waitcnt lgkmcnt(2)
	v_mfma_f32_32x32x16_bf16 v[114:129], v[230:233], v[154:157], v[114:129]
	v_fma_f32 v10, v89, v5, v4
	v_exp_f32_e32 v86, v10
	v_add_f32_e32 v17, v15, v101
	v_cvt_pk_bf16_f32 v9, v15, v16
	v_pk_add_f32 v[10:11], v[16:17], v[86:87]
	s_nop 0
	v_pk_add_f32 v[88:89], v[10:11], v[10:11] op_sel_hi:[0,1]
	v_fma_f32 v10, v106, v5, v4
	s_waitcnt lgkmcnt(1)
	v_mfma_f32_32x32x16_bf16 v[130:145], v[234:237], v[158:161], v[130:145]
	v_exp_f32_e32 v87, v10
	v_fma_f32 v10, v90, v5, v4
	v_exp_f32_e32 v248, v10
	v_fma_f32 v10, v107, v5, v4
	v_exp_f32_e32 v90, v10
	v_fma_f32 v10, v91, v5, v4
	v_exp_f32_e32 v88, v10
	v_fma_f32 v10, v108, v5, v4
	s_waitcnt lgkmcnt(0)
	v_mfma_f32_32x32x16_bf16 v[114:129], v[238:241], v[158:161], v[114:129]
	v_exp_f32_e32 v107, v10
	v_fma_f32 v10, v92, v5, v4
	v_add_f32_e32 v91, v87, v248
	v_exp_f32_e32 v108, v10
	v_pk_add_f32 v[10:11], v[90:91], v[88:89]
	v_fma_f32 v91, v112, v5, v4
	v_pk_add_f32 v[102:103], v[10:11], v[10:11] op_sel_hi:[0,1]
	v_fma_f32 v10, v109, v5, v4
	v_exp_f32_e32 v104, v10
	v_fma_f32 v10, v93, v5, v4
	v_exp_f32_e32 v102, v10
	v_add_u32_e32 v10, s76, v211
	v_add3_u32 v17, v10, v203, v204
	v_add_u32_e32 v89, v17, v202
	ds_read_b64_tr_b16 v[10:11], v89 offset:8192
	ds_read_b64_tr_b16 v[12:13], v89 offset:9216
	v_add_u32_e32 v109, v17, v213
	ds_read_b64_tr_b16 v[14:15], v109 offset:8256
	ds_read_b64_tr_b16 v[16:17], v109 offset:9280
	ds_read_b64_tr_b16 v[82:83], v89 offset:10240
	ds_read_b64_tr_b16 v[84:85], v89 offset:11264
	s_waitcnt lgkmcnt(4)
	v_mfma_f32_32x32x16_bf16 v[66:81], v[10:13], v[6:9], v[66:81]
	v_fma_f32 v10, v110, v5, v4
	v_exp_f32_e32 v93, v10
	v_fma_f32 v10, v111, v5, v4
	v_exp_f32_e32 v92, v10
	v_exp_f32_e32 v110, v91
	v_add_f32_e32 v105, v107, v108
	ds_read_b64_tr_b16 v[10:11], v109 offset:10304
	ds_read_b64_tr_b16 v[12:13], v109 offset:11328
	s_waitcnt lgkmcnt(4)
	v_mfma_f32_32x32x16_bf16 v[50:65], v[14:17], v[6:9], v[50:65]
	v_fma_f32 v6, v113, v5, v4
	v_exp_f32_e32 v106, v6
	v_cvt_pk_bf16_f32 v6, v87, v90
	v_cvt_pk_bf16_f32 v7, v107, v104
	v_cvt_pk_bf16_f32 v8, v93, v92
	v_cvt_pk_bf16_f32 v9, v110, v106
	v_pk_add_f32 v[14:15], v[104:105], v[102:103]
	s_waitcnt lgkmcnt(2)
	v_mfma_f32_32x32x16_bf16 v[66:81], v[82:85], v[6:9], v[66:81]
	v_add_f32_e64 v90, v14, v14
	v_add_f32_e64 v91, v14, v15
	v_fma_f32 v14, v94, v5, v4
	v_exp_f32_e32 v94, v14
	ds_read_b64_tr_b16 v[14:15], v89 offset:12288
	ds_read_b64_tr_b16 v[16:17], v89 offset:13312
	v_fma_f32 v82, v95, v5, v4
	v_exp_f32_e32 v90, v82
	v_add_f32_e32 v93, v93, v94
	s_waitcnt lgkmcnt(2)
	v_mfma_f32_32x32x16_bf16 v[50:65], v[10:13], v[6:9], v[50:65]
	v_cvt_pk_bf16_f32 v6, v246, v2
	v_cvt_pk_bf16_f32 v7, v247, v98
	v_cvt_pk_bf16_f32 v8, v99, v100
	v_cvt_pk_bf16_f32 v9, v101, v86
	ds_read_b64_tr_b16 v[10:11], v89 offset:14336
	ds_read_b64_tr_b16 v[12:13], v89 offset:15360
	v_pk_add_f32 v[82:83], v[92:93], v[90:91]
	v_fma_f32 v2, v96, v5, v4
	s_waitcnt lgkmcnt(2)
	v_mfma_f32_32x32x16_bf16 v[66:81], v[14:17], v[6:9], v[66:81]
	ds_read_b64_tr_b16 v[14:15], v109 offset:12352
	ds_read_b64_tr_b16 v[16:17], v109 offset:13376
	v_add_f32_e64 v86, v82, v82
	v_add_f32_e64 v87, v82, v83
	v_fmac_f32_e32 v4, v97, v5
	ds_read_b64_tr_b16 v[82:83], v109 offset:14400
	ds_read_b64_tr_b16 v[84:85], v109 offset:15424
	v_exp_f32_e32 v2, v2
	v_exp_f32_e32 v86, v4
	v_cvt_pk_bf16_f32 v4, v248, v88
	s_waitcnt lgkmcnt(2)
	v_mfma_f32_32x32x16_bf16 v[50:65], v[14:17], v[6:9], v[50:65]
	v_cvt_pk_bf16_f32 v5, v108, v102
	v_cvt_pk_bf16_f32 v6, v94, v90
	v_cvt_pk_bf16_f32 v7, v2, v86
	v_add_f32_e32 v107, v110, v2
	v_add_f32_e64 v8, v106, v86
	v_add_f32_e64 v9, v107, v87
	v_add_f32_e32 v2, v8, v9
	v_mfma_f32_32x32x16_bf16 v[66:81], v[10:13], v[4:7], v[66:81]
	v_add_f32_e32 v214, v214, v2
	s_waitcnt lgkmcnt(0)
	v_mfma_f32_32x32x16_bf16 v[50:65], v[82:85], v[4:7], v[50:65]
	s_add_i32 s76, s74, 2
	s_cmp_ge_u32 s76, s51
	s_cbranch_scc0 .LBB0_781

.LBB0_781:
	s_add_i32 s4, s74, 6
	s_cmp_ge_u32 s4, s51
	s_waitcnt vmcnt(1)
	ds_write_b128 v205, v[162:165]
	s_waitcnt vmcnt(0)
	ds_write_b128 v212, v[166:169] offset:8192
	s_waitcnt lgkmcnt(0)
	s_barrier
	s_cbranch_scc1 .LBB0_783
	s_cmp_gt_u32 s4, s69
	s_cselect_b64 s[8:9], -1, 0
	s_add_i32 s5, s52, -1
	s_and_b64 s[8:9], s[8:9], exec
	s_cselect_b32 s4, s5, s4
	s_cselect_b32 s16, 0x1000, s65
	s_cselect_b32 s8, s64, 0x500
	s_lshl_b32 s4, s4, 6
	s_mov_b32 s9, s17
	v_mad_i64_i32 v[4:5], s[4:5], s4, v199, v[192:193]
	v_lshl_add_u64 v[6:7], v[4:5], 0, s[8:9]
	v_lshl_add_u64 v[4:5], v[4:5], 0, s[16:17]
	global_load_dwordx4 v[162:165], v[6:7], off
	global_load_dwordx4 v[166:169], v[4:5], off

.LBB0_785:
	s_add_i32 s10, s52, 3
	s_cmp_gt_u32 s76, s69
	s_cselect_b64 s[8:9], -1, 0
	s_and_b64 vcc, s[8:9], exec
	s_cselect_b32 s8, s10, s76
	v_lshl_or_b32 v2, s8, 6, v194
	s_mov_b64 s[10:11], -1
	s_cbranch_vccnz .LBB0_789
	v_lshrrev_b32_e32 v4, s76, v196
	v_and_b32_e32 v4, 1, v4
	v_mov_b64_e32 v[82:83], v[114:115]
	v_mov_b64_e32 v[98:99], v[130:131]
	v_cmp_eq_u32_e64 s[8:9], 1, v4
	s_cmp_lg_u32 s71, s74
	v_mov_b64_e32 v[84:85], v[116:117]
	v_mov_b64_e32 v[86:87], v[118:119]
	v_mov_b64_e32 v[88:89], v[120:121]
	v_mov_b64_e32 v[90:91], v[122:123]
	v_mov_b64_e32 v[92:93], v[124:125]
	v_mov_b64_e32 v[94:95], v[126:127]
	v_mov_b64_e32 v[96:97], v[128:129]
	v_mov_b64_e32 v[100:101], v[132:133]
	v_mov_b64_e32 v[102:103], v[134:135]
	v_mov_b64_e32 v[104:105], v[136:137]
	v_mov_b64_e32 v[106:107], v[138:139]
	v_mov_b64_e32 v[108:109], v[140:141]
	v_mov_b64_e32 v[110:111], v[142:143]
	v_mov_b64_e32 v[112:113], v[144:145]
	s_cbranch_scc1 .LBB0_788
	v_cmp_le_i32_e32 vcc, v2, v190
	v_or_b32_e32 v4, 32, v2
	s_nop 0
	v_cndmask_b32_e32 v98, v186, v130, vcc
	v_cmp_le_i32_e32 vcc, v4, v190
	v_or_b32_e32 v4, 33, v2
	s_nop 0
	v_cndmask_b32_e32 v82, v186, v114, vcc
	v_cmp_lt_i32_e32 vcc, v2, v190
	s_nop 1
	v_cndmask_b32_e32 v99, v186, v131, vcc
	v_cmp_le_i32_e32 vcc, v4, v190
	v_or_b32_e32 v4, 2, v2
	s_nop 0
	v_cndmask_b32_e32 v83, v186, v115, vcc
	v_cmp_le_i32_e32 vcc, v4, v190
	v_or_b32_e32 v4, 34, v2
	s_nop 0
	v_cndmask_b32_e32 v100, v186, v132, vcc
	v_cmp_le_i32_e32 vcc, v4, v190
	v_or_b32_e32 v4, 3, v2
	s_nop 0
	v_cndmask_b32_e32 v84, v186, v116, vcc
	v_cmp_le_i32_e32 vcc, v4, v190
	v_or_b32_e32 v4, 35, v2
	s_nop 0
	v_cndmask_b32_e32 v101, v186, v133, vcc
	v_cmp_le_i32_e32 vcc, v4, v190
	v_or_b32_e32 v4, 8, v2
	s_nop 0
	v_cndmask_b32_e32 v85, v186, v117, vcc
	v_cmp_le_i32_e32 vcc, v4, v190
	v_or_b32_e32 v4, 40, v2
	s_nop 0
	v_cndmask_b32_e32 v102, v186, v134, vcc
	v_cmp_le_i32_e32 vcc, v4, v190
	v_or_b32_e32 v4, 9, v2
	s_nop 0
	v_cndmask_b32_e32 v86, v186, v118, vcc
	v_cmp_le_i32_e32 vcc, v4, v190
	v_or_b32_e32 v4, 41, v2
	s_nop 0
	v_cndmask_b32_e32 v103, v186, v135, vcc
	v_cmp_le_i32_e32 vcc, v4, v190
	v_or_b32_e32 v4, 10, v2
	s_nop 0
	v_cndmask_b32_e32 v87, v186, v119, vcc
	v_cmp_le_i32_e32 vcc, v4, v190
	v_or_b32_e32 v4, 42, v2
	s_nop 0
	v_cndmask_b32_e32 v104, v186, v136, vcc
	v_cmp_le_i32_e32 vcc, v4, v190
	v_or_b32_e32 v4, 11, v2
	s_nop 0
	v_cndmask_b32_e32 v88, v186, v120, vcc
	v_cmp_le_i32_e32 vcc, v4, v190
	v_or_b32_e32 v4, 43, v2
	s_nop 0
	v_cndmask_b32_e32 v105, v186, v137, vcc
	v_cmp_le_i32_e32 vcc, v4, v190
	v_or_b32_e32 v4, 16, v2
	s_nop 0
	v_cndmask_b32_e32 v89, v186, v121, vcc
	v_cmp_le_i32_e32 vcc, v4, v190
	v_or_b32_e32 v4, 48, v2
	s_nop 0
	v_cndmask_b32_e32 v106, v186, v138, vcc
	v_cmp_le_i32_e32 vcc, v4, v190
	v_or_b32_e32 v4, 17, v2
	s_nop 0
	v_cndmask_b32_e32 v90, v186, v122, vcc
	v_cmp_le_i32_e32 vcc, v4, v190
	v_or_b32_e32 v4, 49, v2
	s_nop 0
	v_cndmask_b32_e32 v107, v186, v139, vcc
	v_cmp_le_i32_e32 vcc, v4, v190
	v_or_b32_e32 v4, 18, v2
	s_nop 0
	v_cndmask_b32_e32 v91, v186, v123, vcc
	v_cmp_le_i32_e32 vcc, v4, v190
	v_or_b32_e32 v4, 50, v2
	s_nop 0
	v_cndmask_b32_e32 v108, v186, v140, vcc
	v_cmp_le_i32_e32 vcc, v4, v190
	v_or_b32_e32 v4, 19, v2
	s_nop 0
	v_cndmask_b32_e32 v92, v186, v124, vcc
	v_cmp_le_i32_e32 vcc, v4, v190
	v_or_b32_e32 v4, 51, v2
	s_nop 0
	v_cndmask_b32_e32 v109, v186, v141, vcc
	v_cmp_le_i32_e32 vcc, v4, v190
	v_or_b32_e32 v4, 24, v2
	s_nop 0
	v_cndmask_b32_e32 v93, v186, v125, vcc
	v_cmp_le_i32_e32 vcc, v4, v190
	v_or_b32_e32 v4, 56, v2
	s_nop 0
	v_cndmask_b32_e32 v110, v186, v142, vcc
	v_cmp_le_i32_e32 vcc, v4, v190
	v_or_b32_e32 v4, 25, v2
	s_nop 0
	v_cndmask_b32_e32 v94, v186, v126, vcc
	v_cmp_le_i32_e32 vcc, v4, v190
	v_or_b32_e32 v4, 57, v2
	s_nop 0
	v_cndmask_b32_e32 v111, v186, v143, vcc
	v_cmp_le_i32_e32 vcc, v4, v190
	v_or_b32_e32 v4, 26, v2
	s_nop 0
	v_cndmask_b32_e32 v95, v186, v127, vcc
	v_cmp_le_i32_e32 vcc, v4, v190
	v_or_b32_e32 v4, 58, v2
	s_nop 0
	v_cndmask_b32_e32 v112, v186, v144, vcc
	v_cmp_le_i32_e32 vcc, v4, v190
	v_or_b32_e32 v4, 27, v2
	s_nop 0
	v_cndmask_b32_e32 v96, v186, v128, vcc
	v_cmp_le_i32_e32 vcc, v4, v190
	v_or_b32_e32 v4, 59, v2
	s_nop 0
	v_cndmask_b32_e32 v113, v186, v145, vcc
	v_cmp_le_i32_e32 vcc, v4, v190
	s_nop 1
	v_cndmask_b32_e32 v97, v186, v129, vcc

; #define LAS __attribute__((address_space(3)))
; #define MFMA32(a, b, c) __builtin_amdgcn_mfma_f32_32x32x16_bf16((a), (b), (c), 0, 0, 0)
; DI float fexp2(float x) { return __builtin_amdgcn_exp2f(x); }
; DI s16x4 vtr(const LAS unsigned char* p) { return __builtin_bit_cast(s16x4, __builtin_amdgcn_ds_read_tr16_b64_v4i16((LAS v4i16_t*)p)); }
; DI void flash_qk(const LAS unsigned char* kb, const bf16x8 (&qf)[4], f32x16& p0, f32x16& p1, int r32, int h) {
;     ...
;     for (int s = 0; s < 4; ++s) {
;         const int off = r32 * 128 + (((2 * s + h) ^ sw) << 4);
;         const bf16x8 a0 = *(const LAS bf16x8*)(kb + off), a1 = *(const LAS bf16x8*)(kb + off + 4096);
;         p0 = MFMA32(a0, qf[s], p0); p1 = MFMA32(a1, qf[s], p1);
;     }
; DI void flash_pv(FState& st, f32x16& p0, f32x16& p1, bool rowon, const LAS unsigned char* vb, int lane) {
;     ...
;     const float cl = rowon ? SM_C : 0.0f;
;     const float bl = rowon ? ((st.m == NINF) ? 0.0f : -st.m * SM_C) : NINF;
;     float sum = 0.f;
; #pragma unroll
;     for (int r = 0; r < 16; ++r) { p0[r] = fexp2(__builtin_fmaf(p0[r], cl, bl)); p1[r] = fexp2(__builtin_fmaf(p1[r], cl, bl)); sum += p0[r] + p1[r]; }
;     st.l += sum;
;     const int h = lane >> 5;
;     const int vx = (((lane & 15) >> 3) & 1) * 64;
;     const LAS unsigned char* vp = vb + (4 * h + ((lane & 15) >> 2)) * 128 + ((lane >> 4) & 1) * 32 + (lane & 3) * 8;
; #pragma unroll
;     for (int sub = 0; sub < 2; ++sub)
; #pragma unroll
;         for (int s2 = 0; s2 < 2; ++s2) {
;             const bf16x8 pf = pack8h(sub ? p1 : p0, s2);
;             const LAS unsigned char* vq = vp + (32 * sub + 16 * s2) * 128;
;             { const s16x4 lo = vtr(vq + vx), hi = vtr(vq + 1024 + vx); const bf16x8 vf = {lo[0], lo[1], lo[2], lo[3], hi[0], hi[1], hi[2], hi[3]}; st.o0 = MFMA32(vf, pf, st.o0); }
;             { const s16x4 lo = vtr(vq + (64 - vx)), hi = vtr(vq + 1024 + (64 - vx)); const bf16x8 vf = {lo[0], lo[1], lo[2], lo[3], hi[0], hi[1], hi[2], hi[3]}; st.o1 = MFMA32(vf, pf, st.o1); }
.LBB0_799:
	s_or_b64 exec, exec, s[4:5]
	ds_read_b128 v[226:229], v221
	ds_read_b128 v[230:233], v221 offset:4096
	ds_read_b128 v[234:237], v222
	ds_read_b128 v[238:241], v222 offset:4096
	v_fma_f32 v2, v98, v5, v4
	v_exp_f32_e32 v246, v2
	v_fma_f32 v2, v82, v5, v4
	v_exp_f32_e32 v247, v2
	v_fma_f32 v2, v99, v5, v4
	v_exp_f32_e32 v10, v2
	s_waitcnt lgkmcnt(3)
	v_mfma_f32_32x32x16_bf16 v[130:145], v[226:229], v[146:149], 0
	v_fma_f32 v2, v83, v5, v4
	v_exp_f32_e32 v2, v2
	v_add_f32_e32 v11, v246, v247
	v_pk_add_f32 v[6:7], v[10:11], v[2:3]
	s_nop 0
	v_pk_add_f32 v[98:99], v[6:7], v[6:7] op_sel_hi:[0,1]
	s_waitcnt lgkmcnt(2)
	v_mfma_f32_32x32x16_bf16 v[114:129], v[230:233], v[146:149], 0
	ds_read_b128 v[226:229], v223
	ds_read_b128 v[230:233], v223 offset:4096
	v_fma_f32 v6, v100, v5, v4
	v_exp_f32_e32 v11, v6
	v_fma_f32 v6, v84, v5, v4
	v_exp_f32_e32 v248, v6
	v_fma_f32 v6, v101, v5, v4
	v_exp_f32_e32 v12, v6
	v_fma_f32 v6, v85, v5, v4
	v_exp_f32_e32 v98, v6
	s_waitcnt lgkmcnt(3)
	v_mfma_f32_32x32x16_bf16 v[130:145], v[234:237], v[150:153], v[130:145]
	v_add_f32_e32 v13, v11, v248
	v_cvt_pk_bf16_f32 v10, v246, v10
	v_cvt_pk_bf16_f32 v11, v11, v12
	v_pk_add_f32 v[6:7], v[12:13], v[98:99]
	s_nop 0
	v_pk_add_f32 v[100:101], v[6:7], v[6:7] op_sel_hi:[0,1]
	v_fma_f32 v6, v102, v5, v4
	v_exp_f32_e32 v13, v6
	s_waitcnt lgkmcnt(2)
	v_mfma_f32_32x32x16_bf16 v[114:129], v[238:241], v[150:153], v[114:129]
	ds_read_b128 v[234:237], v224
	ds_read_b128 v[238:241], v224 offset:4096
	v_fma_f32 v6, v86, v5, v4
	v_exp_f32_e32 v99, v6
	v_fma_f32 v6, v103, v5, v4
	v_exp_f32_e32 v14, v6
	v_fma_f32 v6, v87, v5, v4
	v_exp_f32_e32 v100, v6
	v_add_f32_e32 v15, v13, v99
	v_cvt_pk_bf16_f32 v12, v13, v14
	s_waitcnt lgkmcnt(3)
	v_mfma_f32_32x32x16_bf16 v[130:145], v[226:229], v[154:157], v[130:145]
	v_pk_add_f32 v[6:7], v[14:15], v[100:101]
	s_nop 0
	v_pk_add_f32 v[86:87], v[6:7], v[6:7] op_sel_hi:[0,1]
	v_fma_f32 v6, v104, v5, v4
	v_exp_f32_e32 v15, v6
	v_fma_f32 v6, v88, v5, v4
	v_exp_f32_e32 v101, v6
	v_fma_f32 v6, v105, v5, v4
	s_waitcnt lgkmcnt(2)
	v_mfma_f32_32x32x16_bf16 v[114:129], v[230:233], v[154:157], v[114:129]
	v_exp_f32_e32 v16, v6
	v_fma_f32 v6, v89, v5, v4
	v_exp_f32_e32 v86, v6
	v_add_f32_e32 v17, v15, v101
	v_cvt_pk_bf16_f32 v13, v15, v16
	v_pk_add_f32 v[6:7], v[16:17], v[86:87]
	s_nop 0
	v_pk_add_f32 v[88:89], v[6:7], v[6:7] op_sel_hi:[0,1]
	s_waitcnt lgkmcnt(1)
	v_mfma_f32_32x32x16_bf16 v[130:145], v[234:237], v[158:161], v[130:145]
	v_fma_f32 v6, v106, v5, v4
	v_exp_f32_e32 v87, v6
	v_fma_f32 v6, v90, v5, v4
	v_exp_f32_e32 v249, v6
	v_fma_f32 v6, v107, v5, v4
	v_exp_f32_e32 v90, v6
	v_fma_f32 v6, v91, v5, v4
	v_exp_f32_e32 v88, v6
	s_waitcnt lgkmcnt(0)
	v_mfma_f32_32x32x16_bf16 v[114:129], v[238:241], v[158:161], v[114:129]
	v_fma_f32 v6, v108, v5, v4
	v_exp_f32_e32 v107, v6
	v_fma_f32 v6, v92, v5, v4
	v_add_f32_e32 v91, v87, v249
	v_exp_f32_e32 v108, v6
	v_pk_add_f32 v[6:7], v[90:91], v[88:89]
	v_fma_f32 v91, v112, v5, v4
	v_pk_add_f32 v[102:103], v[6:7], v[6:7] op_sel_hi:[0,1]
	v_fma_f32 v6, v109, v5, v4
	v_exp_f32_e32 v104, v6
	v_fma_f32 v6, v93, v5, v4
	v_exp_f32_e32 v102, v6
	ds_read_b64_tr_b16 v[6:7], v218 offset:40960
	ds_read_b64_tr_b16 v[8:9], v218 offset:41984
	ds_read_b64_tr_b16 v[14:15], v217 offset:41024
	ds_read_b64_tr_b16 v[16:17], v217 offset:42048
	ds_read_b64_tr_b16 v[82:83], v218 offset:43008
	ds_read_b64_tr_b16 v[84:85], v218 offset:44032
	s_waitcnt lgkmcnt(4)
	v_mfma_f32_32x32x16_bf16 v[66:81], v[6:9], v[10:13], v[66:81]
	v_fma_f32 v6, v110, v5, v4
	v_exp_f32_e32 v89, v6
	v_fma_f32 v6, v111, v5, v4
	v_exp_f32_e32 v92, v6
	v_exp_f32_e32 v109, v91
	v_add_f32_e32 v105, v107, v108
	ds_read_b64_tr_b16 v[6:7], v217 offset:43072
	ds_read_b64_tr_b16 v[8:9], v217 offset:44096
	s_waitcnt lgkmcnt(4)
	v_mfma_f32_32x32x16_bf16 v[50:65], v[14:17], v[10:13], v[50:65]
	v_fma_f32 v10, v113, v5, v4
	v_exp_f32_e32 v106, v10
	v_cvt_pk_bf16_f32 v10, v87, v90
	v_cvt_pk_bf16_f32 v11, v107, v104
	v_cvt_pk_bf16_f32 v12, v89, v92
	v_cvt_pk_bf16_f32 v13, v109, v106
	v_pk_add_f32 v[14:15], v[104:105], v[102:103]
	s_waitcnt lgkmcnt(2)
	v_mfma_f32_32x32x16_bf16 v[66:81], v[82:85], v[10:13], v[66:81]
	v_add_f32_e64 v90, v14, v14
	v_add_f32_e64 v91, v14, v15
	v_fma_f32 v14, v94, v5, v4
	v_exp_f32_e32 v94, v14
	ds_read_b64_tr_b16 v[14:15], v218 offset:45056
	ds_read_b64_tr_b16 v[16:17], v218 offset:46080
	v_fma_f32 v82, v95, v5, v4
	v_exp_f32_e32 v90, v82
	v_add_f32_e32 v93, v89, v94
	s_waitcnt lgkmcnt(2)
	v_mfma_f32_32x32x16_bf16 v[50:65], v[6:9], v[10:13], v[50:65]
	v_cvt_pk_bf16_f32 v6, v247, v2
	v_cvt_pk_bf16_f32 v7, v248, v98
	v_cvt_pk_bf16_f32 v8, v99, v100
	v_cvt_pk_bf16_f32 v9, v101, v86
	ds_read_b64_tr_b16 v[10:11], v218 offset:47104
	ds_read_b64_tr_b16 v[12:13], v218 offset:48128
	v_pk_add_f32 v[82:83], v[92:93], v[90:91]
	v_fma_f32 v2, v96, v5, v4
	s_waitcnt lgkmcnt(2)
	v_mfma_f32_32x32x16_bf16 v[66:81], v[14:17], v[6:9], v[66:81]
	ds_read_b64_tr_b16 v[14:15], v217 offset:45120
	ds_read_b64_tr_b16 v[16:17], v217 offset:46144
	v_add_f32_e64 v86, v82, v82
	v_add_f32_e64 v87, v82, v83
	v_fmac_f32_e32 v4, v97, v5
	ds_read_b64_tr_b16 v[82:83], v217 offset:47168
	ds_read_b64_tr_b16 v[84:85], v217 offset:48192
	v_exp_f32_e32 v2, v2
	v_exp_f32_e32 v86, v4
	v_cvt_pk_bf16_f32 v4, v249, v88
	s_waitcnt lgkmcnt(2)
	v_mfma_f32_32x32x16_bf16 v[50:65], v[14:17], v[6:9], v[50:65]
	v_cvt_pk_bf16_f32 v5, v108, v102
	v_cvt_pk_bf16_f32 v6, v94, v90
	v_cvt_pk_bf16_f32 v7, v2, v86
	v_add_f32_e32 v107, v109, v2
	v_add_f32_e64 v8, v106, v86
	v_add_f32_e64 v9, v107, v87
	v_add_f32_e32 v2, v8, v9
	v_mfma_f32_32x32x16_bf16 v[66:81], v[10:13], v[4:7], v[66:81]
	v_add_f32_e32 v214, v214, v2
	s_waitcnt lgkmcnt(0)
	v_mfma_f32_32x32x16_bf16 v[50:65], v[82:85], v[4:7], v[50:65]
	s_add_i32 s52, s52, -3
	s_andn2_b64 vcc, exec, s[6:7]
	s_add_i32 s53, s53, 0xc000
	s_cbranch_vccz .LBB0_712
